# prep stage 1: first prefix-sum step as lw + row_shr:1(lw) on the rounded log-decay (uncontracted form of the source expression), 12 fewer instructions
# speedup vs baseline: 1.0038x; 1.0038x over previous
; __device__ __forceinline__ void phase_prep(const Params& p, unsigned char* shm) {
;     ...
;     auto zload = [&](int it) {
;         const int rw0 = (it >> 4) * 64;
; #pragma unroll
;         for (int i = 0; i < 6; ++i) { int grow = rw0 - 1 + zrow[i]; grow = grow < 0 ? 0 : grow; zpre[i] = *(const u32x4*)(p.Z + (size_t)grow * LDZ + ZC_S + zcol[i]); }
;     };
;     if ((int)blockIdx.x < NCH * 16) zload(blockIdx.x);
;     for (int item = blockIdx.x; item < NCH * 16; item += gridDim.x) {
;         int tid = threadIdx.x; asm volatile("" : "+v"(tid));
;         const int lane = tid & 63, wid = __builtin_amdgcn_readfirstlane(tid >> 6), fr = lane & 15, fq = lane >> 4;
;         const int h = item & 15, cidx = item >> 4, row0 = cidx * 64; const size_t chbase = (size_t)item * 4096;
;         const int crow = tid >> 3, cseg = (tid & 7) * 8;
;         {
;             const bool first = seq_first(row0);
; #pragma unroll
;             for (int i = 0; i < 6; ++i) {
;                 if (zlds[i] >= 0) {
;                     u32x4 v = zpre[i];
;                     if ((i == 0 || i == 2) && first && zrow[i] == 0) { v = (u32x4){0u, 0u, 0u, 0u};
;                         if (row0 >= MP) { const float* sp = p.st_shift + (size_t)((row0 - MP) >> 6) * NSHIFT + zcol[i]; const f32x4 a = *(const f32x4*)sp, b = *(const f32x4*)(sp + 4);
;                             v = (u32x4){pk_bf16(a[0], a[1]), pk_bf16(a[2], a[3]), pk_bf16(b[0], b[1]), pk_bf16(b[2], b[3])}; } }
;                     *(u32x4*)(shm + zlds[i]) = v; } }
;             const int nitem = item + (int)gridDim.x;
;             zload(nitem < NCH * 16 ? nitem : item);
;         }
;         LDS_BARRIER();
;         {
;             const int j = tid >> 3, p8 = tid & 7;
; #pragma unroll
;             for (int isa = 0; isa < 2; ++isa) {
;                 const int c = isa * 64 + 8 * p8;
;                 const u32x4 cu = *(const u32x4*)(zh + (j + 1) * LZH + c), pu = *(const u32x4*)(zh + j * LZH + c);
;                 const f32x4 m0 = *(const f32x4*)(prm + 512 + c), m1 = *(const f32x4*)(prm + 512 + c + 4);
;                 const unsigned cw[4] = {cu.x, cu.y, cu.z, cu.w}, pw[4] = {pu.x, pu.y, pu.z, pu.w};
;                 float x[8];
; #pragma unroll
;                 for (int e = 0; e < 4; ++e) { const float c0 = bf_lo(cw[e]), c1 = bf_hi(cw[e]), mA = e < 2 ? m0[2 * e] : m1[2 * e - 4], mB = e < 2 ? m0[2 * e + 1] : m1[2 * e - 3];
.LBB0_189:
	s_or_b64 exec, exec, s[18:19]
	s_add_i32 s70, s26, s38
	s_cmpk_gt_i32 s70, 0x21ff
	s_cselect_b64 s[42:43], -1, 0
	s_cmpk_lt_i32 s70, 0x2200
	s_cselect_b32 s18, s70, s26
	s_mov_b64 s[20:21], s[88:89]
	s_lshl_b32 s18, s18, 2
	s_andn2_b32 s18, s18, 63
	s_add_i32 s22, s18, -1
	v_add_u32_e32 v0, s22, v123
	v_max_i32_e32 v0, 0, v0
	s_mov_b64 s[18:19], s[90:91]
	s_waitcnt vmcnt(6) lgkmcnt(0)
	v_mov_b64_e32 v[8:9], s[20:21]
	v_mad_u64_u32 v[0:1], s[20:21], v0, s3, v[8:9]
	v_lshlrev_b32_e32 v126, 1, v122
	v_add_u32_e32 v2, s22, v176
	v_lshl_add_u64 v[0:1], v[0:1], 0, v[126:127]
	v_max_i32_e32 v2, 0, v2
	v_add_co_u32_e32 v0, vcc, s49, v0
	v_mad_u64_u32 v[2:3], s[20:21], v2, s3, v[8:9]
	v_mov_b32_e32 v137, v127
	v_addc_co_u32_e32 v1, vcc, 0, v1, vcc
	v_lshl_add_u64 v[2:3], v[2:3], 0, v[136:137]
	v_add_co_u32_e32 v2, vcc, s49, v2
	v_mov_b32_e32 v139, v127
	s_nop 0
	v_addc_co_u32_e32 v3, vcc, 0, v3, vcc
	global_load_dwordx4 v[20:23], v[0:1], off offset:2048
	global_load_dwordx4 v[16:19], v[2:3], off offset:2048
	v_add_u32_e32 v0, s22, v121
	v_max_i32_e32 v0, 0, v0
	v_mad_u64_u32 v[0:1], s[20:21], v0, s3, v[8:9]
	v_add_u32_e32 v2, s22, v175
	v_lshl_add_u64 v[0:1], v[124:125], 1, v[0:1]
	v_max_i32_e32 v2, 0, v2
	v_add_co_u32_e32 v0, vcc, s49, v0
	v_mad_u64_u32 v[2:3], s[20:21], v2, s3, v[8:9]
	v_add_u32_sdwa v10, s22, v157 dst_sel:DWORD dst_unused:UNUSED_PAD src0_sel:DWORD src1_sel:WORD_1
	v_addc_co_u32_e32 v1, vcc, 0, v1, vcc
	v_lshl_add_u64 v[2:3], v[2:3], 0, v[138:139]
	v_max_i32_e32 v10, 0, v10
	v_add_co_u32_e32 v2, vcc, s49, v2
	v_mad_u64_u32 v[10:11], s[20:21], v10, s3, v[8:9]
	v_mov_b32_e32 v141, v127
	v_add_u32_sdwa v12, s22, v174 dst_sel:DWORD dst_unused:UNUSED_PAD src0_sel:DWORD src1_sel:WORD_1
	v_addc_co_u32_e32 v3, vcc, 0, v3, vcc
	v_lshl_add_u64 v[10:11], v[10:11], 0, v[140:141]
	v_max_i32_e32 v12, 0, v12
	v_add_co_u32_e32 v10, vcc, s49, v10
	v_mad_u64_u32 v[8:9], s[20:21], v12, s3, v[8:9]
	v_mov_b32_e32 v143, v127
	v_lshlrev_b32_e32 v188, 3, v187
	v_addc_co_u32_e32 v11, vcc, 0, v11, vcc
	v_lshl_add_u64 v[8:9], v[8:9], 0, v[142:143]
	v_ashrrev_i32_e32 v186, 3, v187
	v_and_b32_e32 v32, 56, v188
	v_add_co_u32_e32 v8, vcc, s49, v8
	v_mul_lo_u32 v24, v186, s48
	s_nop 0
	v_addc_co_u32_e32 v9, vcc, 0, v9, vcc
	v_lshlrev_b32_e32 v144, 1, v32
	global_load_dwordx4 v[4:7], v[0:1], off offset:2048
	s_nop 0
	global_load_dwordx4 v[0:3], v[2:3], off offset:2048
	s_nop 0
	global_load_dwordx4 v[12:15], v[10:11], off offset:2048
	s_nop 0
	global_load_dwordx4 v[8:11], v[8:9], off offset:2048
	s_waitcnt lgkmcnt(0)
	s_barrier
	v_add3_u32 v45, 0, v24, v144
	ds_read_b128 v[24:27], v45 offset:37136
	ds_read_b128 v[28:31], v45 offset:36864
	v_lshlrev_b32_e32 v46, 2, v32
	v_add_u32_e32 v32, 0, v46
	v_add_u32_e32 v47, 0x25000, v32
	ds_read_b128 v[32:35], v47
	ds_read_b128 v[36:39], v47 offset:16
	s_waitcnt lgkmcnt(3)
	v_lshlrev_b32_e32 v40, 16, v24
	v_and_b32_e32 v41, 0xffff0000, v24
	s_waitcnt lgkmcnt(2)
	v_lshlrev_b32_e32 v42, 16, v28
	v_and_b32_e32 v43, 0xffff0000, v28
	v_lshlrev_b32_e32 v24, 16, v25
	v_and_b32_e32 v25, 0xffff0000, v25
	v_lshlrev_b32_e32 v28, 16, v29
	v_and_b32_e32 v29, 0xffff0000, v29
	v_pk_add_f32 v[28:29], v[28:29], v[24:25] neg_lo:[0,1] neg_hi:[0,1]
	v_pk_add_f32 v[42:43], v[42:43], v[40:41] neg_lo:[0,1] neg_hi:[0,1]
	s_waitcnt lgkmcnt(1)
	v_pk_fma_f32 v[24:25], v[34:35], v[28:29], v[24:25]
	v_lshlrev_b32_e32 v28, 16, v26
	v_and_b32_e32 v29, 0xffff0000, v26
	v_lshlrev_b32_e32 v34, 16, v30
	v_and_b32_e32 v35, 0xffff0000, v30
	v_lshlrev_b32_e32 v26, 16, v27
	v_and_b32_e32 v27, 0xffff0000, v27
	v_lshlrev_b32_e32 v30, 16, v31
	v_and_b32_e32 v31, 0xffff0000, v31
	v_pk_add_f32 v[34:35], v[34:35], v[28:29] neg_lo:[0,1] neg_hi:[0,1]
	v_pk_add_f32 v[30:31], v[30:31], v[26:27] neg_lo:[0,1] neg_hi:[0,1]
	v_pk_fma_f32 v[32:33], v[32:33], v[42:43], v[40:41]
	s_waitcnt lgkmcnt(0)
	v_pk_fma_f32 v[28:29], v[36:37], v[34:35], v[28:29]
	v_pk_fma_f32 v[26:27], v[38:39], v[30:31], v[26:27]
	v_pk_mul_f32 v[32:33], v[32:33], s[2:3] op_sel_hi:[1,0]
	v_pk_mul_f32 v[24:25], v[24:25], s[2:3] op_sel_hi:[1,0]
	v_pk_mul_f32 v[28:29], v[28:29], s[2:3] op_sel_hi:[1,0]
	v_pk_mul_f32 v[26:27], v[26:27], s[2:3] op_sel_hi:[1,0]
	v_exp_f32_e32 v32, v32
	v_exp_f32_e32 v33, v33
	v_exp_f32_e32 v24, v24
	v_exp_f32_e32 v25, v25
	v_exp_f32_e32 v28, v28
	v_exp_f32_e32 v29, v29
	v_exp_f32_e32 v26, v26
	v_exp_f32_e32 v27, v27
	v_pk_add_f32 v[32:33], v[32:33], 1.0 op_sel_hi:[1,0]
	v_pk_add_f32 v[24:25], v[24:25], 1.0 op_sel_hi:[1,0]
	v_pk_add_f32 v[28:29], v[28:29], 1.0 op_sel_hi:[1,0]
	v_pk_add_f32 v[26:27], v[26:27], 1.0 op_sel_hi:[1,0]
	v_rcp_f32_e32 v32, v32
	v_rcp_f32_e32 v33, v33
	v_rcp_f32_e32 v24, v24
	v_rcp_f32_e32 v25, v25
	v_rcp_f32_e32 v28, v28
	v_rcp_f32_e32 v29, v29
	v_rcp_f32_e32 v26, v26
	v_rcp_f32_e32 v27, v27
	v_mul_lo_u32 v44, v186, s50
	v_pk_fma_f32 v[30:31], v[32:33], 2.0, 1.0 op_sel_hi:[1,0,0] neg_lo:[1,0,0] neg_hi:[1,0,0]
	v_pk_fma_f32 v[32:33], v[24:25], 2.0, 1.0 op_sel_hi:[1,0,0] neg_lo:[1,0,0] neg_hi:[1,0,0]
	v_pk_fma_f32 v[28:29], v[28:29], 2.0, 1.0 op_sel_hi:[1,0,0] neg_lo:[1,0,0] neg_hi:[1,0,0]
	v_pk_fma_f32 v[34:35], v[26:27], 2.0, 1.0 op_sel_hi:[1,0,0] neg_lo:[1,0,0] neg_hi:[1,0,0]
	v_cvt_pk_bf16_f32 v24, v30, v31
	v_cvt_pk_bf16_f32 v25, v32, v33
	v_cvt_pk_bf16_f32 v26, v28, v29
	v_cvt_pk_bf16_f32 v27, v34, v35
	v_add3_u32 v44, 0, v44, v144
	ds_read_b128 v[28:31], v45 offset:37264
	ds_write_b128 v44, v[24:27]
	ds_read_b128 v[24:27], v45 offset:36992
	ds_read_b128 v[32:35], v47 offset:256
	ds_read_b128 v[36:39], v47 offset:272
	s_and_b32 s22, s26, 15
	s_lshl_b32 s40, s22, 7
	s_waitcnt lgkmcnt(4)
	v_lshlrev_b32_e32 v40, 16, v28
	v_and_b32_e32 v41, 0xffff0000, v28
	s_waitcnt lgkmcnt(2)
; __device__ __forceinline__ float bf_lo(unsigned u) { return __uint_as_float(u << 16); }
; __device__ __forceinline__ void phase_prep(const Params& p, unsigned char* shm) {
;     ...
;                 if (isa == 0) {
; #pragma unroll
;                     for (int e = 0; e < 4; ++e) { const f32x2 th = tanh2((f32x2){x[2 * e], x[2 * e + 1]}); x[2 * e] = th.x; x[2 * e + 1] = th.y; }
;                 }
;                 *(u32x4*)((isa ? tha : thw) + j * LD + 8 * p8) = (u32x4){pk_bf16(x[0], x[1]), pk_bf16(x[2], x[3]), pk_bf16(x[4], x[5]), pk_bf16(x[6], x[7])};
;             }
;             {
;                 const u32x4 cu = *(const u32x4*)(zs + (j + 1) * LZS + 128 + 8 * p8), pu = *(const u32x4*)(zs + j * LZS + 128 + 8 * p8);
;                 const f32x4 m0 = *(const f32x4*)(prm + 256 + 8 * p8), m1 = *(const f32x4*)(prm + 256 + 8 * p8 + 4);
;                 const unsigned cw[4] = {cu.x, cu.y, cu.z, cu.w}, pw[4] = {pu.x, pu.y, pu.z, pu.w};
;                 float x[8];
; #pragma unroll
;                 for (int e = 0; e < 4; ++e) { const float c0 = bf_lo(cw[e]), c1 = bf_hi(cw[e]), mA = e < 2 ? m0[2 * e] : m1[2 * e - 4], mB = e < 2 ? m0[2 * e + 1] : m1[2 * e - 3];
;                     x[2 * e] = c0 + mA * (bf_lo(pw[e]) - c0); x[2 * e + 1] = c1 + mB * (bf_hi(pw[e]) - c1); }
;                 *(u32x4*)(p.PV + ((size_t)(row0 + j) * 16 + h) * 64 + 8 * p8) = (u32x4){pk_bf16(x[0], x[1]), pk_bf16(x[2], x[3]), pk_bf16(x[4], x[5]), pk_bf16(x[6], x[7])};
;             }
;         }
;         LDS_BARRIER();
;         const int tt = wid & 3, chh = wid >> 2, tk = 16 * tt + fr, row = row0 + tk;
;         f32x4 lw[2], av[2], vm[2], kkv[2], kp[2], rm[2], cs[2]; float nrm = 0.f, rk = 0.f;
;         {
;             f32x4 accd[2], acca[2];
; #pragma unroll
;             for (int n = 0; n < 2; ++n) { accd[n] = (f32x4){0.f, 0.f, 0.f, 0.f}; acca[n] = (f32x4){0.f, 0.f, 0.f, 0.f}; }
; #pragma unroll
;             for (int ks = 0; ks < 2; ++ks) {
;                 const bf16x8 bw = ldfrag(thw, LD, 16 * tt, 32 * ks, fr, fq), ba = ldfrag(tha, LD, 16 * tt, 32 * ks, fr, fq);
; #pragma unroll
;                 for (int n = 0; n < 2; ++n) {
;                     accd[n] = MFMA16(ldfrag(w2P, LD, 32 * chh + 16 * n, 32 * ks, fr, fq), bw, accd[n]);
;                     acca[n] = MFMA16(ldfrag(a2P, LD, 32 * chh + 16 * n, 32 * ks, fr, fq), ba, acca[n]);
;                 }
;             }
	v_lshlrev_b32_e32 v42, 16, v24
	v_and_b32_e32 v43, 0xffff0000, v24
	v_lshlrev_b32_e32 v28, 16, v29
	v_and_b32_e32 v29, 0xffff0000, v29
	v_lshlrev_b32_e32 v24, 16, v25
	v_and_b32_e32 v25, 0xffff0000, v25
	v_pk_add_f32 v[24:25], v[24:25], v[28:29] neg_lo:[0,1] neg_hi:[0,1]
	v_pk_add_f32 v[42:43], v[42:43], v[40:41] neg_lo:[0,1] neg_hi:[0,1]
	s_waitcnt lgkmcnt(1)
	v_pk_fma_f32 v[28:29], v[34:35], v[24:25], v[28:29]
	v_lshlrev_b32_e32 v24, 16, v30
	v_and_b32_e32 v25, 0xffff0000, v30
	v_lshlrev_b32_e32 v34, 16, v26
	v_and_b32_e32 v35, 0xffff0000, v26
	v_pk_add_f32 v[34:35], v[34:35], v[24:25] neg_lo:[0,1] neg_hi:[0,1]
	v_lshlrev_b32_e32 v26, 16, v27
	s_waitcnt lgkmcnt(0)
	v_pk_fma_f32 v[34:35], v[36:37], v[34:35], v[24:25]
	v_lshlrev_b32_e32 v24, 16, v31
	v_and_b32_e32 v25, 0xffff0000, v31
	v_and_b32_e32 v27, 0xffff0000, v27
	v_pk_add_f32 v[26:27], v[26:27], v[24:25] neg_lo:[0,1] neg_hi:[0,1]
	v_pk_fma_f32 v[32:33], v[32:33], v[42:43], v[40:41]
	v_pk_fma_f32 v[30:31], v[38:39], v[26:27], v[24:25]
	v_cvt_pk_bf16_f32 v24, v32, v33
	v_cvt_pk_bf16_f32 v25, v28, v29
	v_cvt_pk_bf16_f32 v26, v34, v35
	v_cvt_pk_bf16_f32 v27, v30, v31
	ds_write_b128 v44, v[24:27] offset:9216
	v_mul_lo_u32 v24, v186, s51
	v_add3_u32 v28, 0, v24, v144
	ds_read_b128 v[24:27], v28 offset:55200
	ds_read_b128 v[28:31], v28 offset:54800
	v_add_u32_e32 v36, s52, v46
	ds_read_b128 v[32:35], v36
	ds_read_b128 v[36:39], v36 offset:16
	v_mov_b32_e32 v145, v127
	s_waitcnt lgkmcnt(3)
	v_lshlrev_b32_e32 v40, 16, v24
	v_and_b32_e32 v41, 0xffff0000, v24
	s_waitcnt lgkmcnt(2)
	v_lshlrev_b32_e32 v42, 16, v28
	v_and_b32_e32 v43, 0xffff0000, v28
	v_lshlrev_b32_e32 v24, 16, v25
	v_and_b32_e32 v25, 0xffff0000, v25
	v_lshlrev_b32_e32 v28, 16, v29
	v_and_b32_e32 v29, 0xffff0000, v29
	v_pk_add_f32 v[28:29], v[28:29], v[24:25] neg_lo:[0,1] neg_hi:[0,1]
	v_pk_add_f32 v[42:43], v[42:43], v[40:41] neg_lo:[0,1] neg_hi:[0,1]
	s_waitcnt lgkmcnt(1)
	v_pk_fma_f32 v[28:29], v[34:35], v[28:29], v[24:25]
	v_lshlrev_b32_e32 v24, 16, v26
	v_and_b32_e32 v25, 0xffff0000, v26
	v_lshlrev_b32_e32 v34, 16, v30
	v_and_b32_e32 v35, 0xffff0000, v30
	v_pk_add_f32 v[34:35], v[34:35], v[24:25] neg_lo:[0,1] neg_hi:[0,1]
	v_lshlrev_b32_e32 v26, 16, v31
	s_waitcnt lgkmcnt(0)
	v_pk_fma_f32 v[34:35], v[36:37], v[34:35], v[24:25]
	v_lshlrev_b32_e32 v24, 16, v27
	v_and_b32_e32 v25, 0xffff0000, v27
	v_and_b32_e32 v27, 0xffff0000, v31
	v_pk_add_f32 v[26:27], v[26:27], v[24:25] neg_lo:[0,1] neg_hi:[0,1]
	v_pk_fma_f32 v[32:33], v[32:33], v[42:43], v[40:41]
	v_pk_fma_f32 v[30:31], v[38:39], v[26:27], v[24:25]
	v_cvt_pk_bf16_f32 v25, v28, v29
	v_add_u32_e32 v28, s24, v186
	v_ashrrev_i32_e32 v29, 31, v28
	v_lshlrev_b64 v[28:29], 11, v[28:29]
	v_lshl_add_u64 v[28:29], s[18:19], 0, v[28:29]
	v_lshl_add_u64 v[28:29], v[28:29], 0, s[40:41]
	s_ashr_i32 s29, s25, 8
	v_and_b32_e32 v185, 15, v187
	v_cvt_pk_bf16_f32 v24, v32, v33
	v_cvt_pk_bf16_f32 v26, v34, v35
	v_cvt_pk_bf16_f32 v27, v30, v31
	v_lshl_add_u64 v[28:29], v[28:29], 0, v[144:145]
	s_lshl_b32 s18, s29, 5
	global_store_dwordx4 v[28:29], v[24:27], off
	v_and_b32_e32 v141, 48, v187
	s_waitcnt lgkmcnt(0)
	s_barrier
	v_or_b32_e32 v24, s18, v185
	v_mul_lo_u32 v145, v24, s50
	v_add3_u32 v60, s5, v141, v145
	s_bfe_u32 s28, s25, 0x20006
	ds_read_b128 v[24:27], v60
	v_lshl_or_b32 v126, s28, 4, v185
	v_mad_u32_u24 v143, v126, s50, 0
	v_add_u32_e32 v189, v143, v141
	v_add3_u32 v64, s7, v141, v145
	ds_read_b128 v[28:31], v189
	ds_read_b128 v[32:35], v64
	ds_read_b128 v[36:39], v189 offset:64
	ds_read_b128 v[40:43], v60 offset:64
	ds_read_b128 v[44:47], v189 offset:9216
	ds_read_b128 v[48:51], v189 offset:9280
	ds_read_b128 v[52:55], v64 offset:64
	ds_read_b128 v[56:59], v60 offset:2304
	ds_read_b128 v[60:63], v60 offset:2368
	s_waitcnt lgkmcnt(4)
	v_mfma_f32_16x16x32_bf16 v[32:35], v[32:35], v[44:47], 0
	v_bfe_u32 v137, v187, 4, 2
	v_lshlrev_b32_e32 v139, 2, v137
	v_or_b32_e32 v146, s18, v139
	v_mfma_f32_16x16x32_bf16 v[24:27], v[24:27], v[28:31], 0
	v_lshlrev_b32_e32 v147, 1, v146
	s_lshl_b32 s20, s28, 8
	s_add_i32 s20, s20, 0
	s_waitcnt lgkmcnt(1)
	v_mfma_f32_16x16x32_bf16 v[28:31], v[56:59], v[28:31], 0
	ds_read_b128 v[56:59], v64 offset:2304
	ds_read_b128 v[64:67], v64 offset:2368
	s_add_i32 s20, s20, 0x1b400
	v_cmp_eq_u32_e64 s[18:19], 15, v185
	v_mfma_f32_16x16x32_bf16 v[72:75], v[52:55], v[48:51], v[32:35]
	v_lshl_add_u32 v191, v146, 2, s20
	s_nop 1
	v_lshlrev_b32_e32 v34, 2, v146
	v_add_u32_e32 v35, 0, v34
	v_mfma_f32_16x16x32_bf16 v[40:43], v[40:43], v[36:39], v[24:27]
	v_add_u32_e32 v32, 0x24900, v35
	ds_read_b128 v[84:87], v32
	s_waitcnt lgkmcnt(3)
	v_mfma_f32_16x16x32_bf16 v[24:27], v[60:63], v[36:39], v[28:31]
	v_lshlrev_b32_e32 v36, 8, v126
	s_nop 1
	v_add_u32_e32 v28, 0x24800, v35
	ds_read_b128 v[28:31], v28
	s_waitcnt lgkmcnt(3)
	v_mfma_f32_16x16x32_bf16 v[44:47], v[56:59], v[44:47], 0
	s_waitcnt lgkmcnt(0)
; __device__ __forceinline__ f32x4 ld_bf4(const bf16_t* p) { const u32x2 u = *(const u32x2*)p; return (f32x4){bf_lo(u.x), bf_hi(u.x), bf_lo(u.y), bf_hi(u.y)}; }
; __device__ __forceinline__ void phase_prep(const Params& p, unsigned char* shm) {
;     ...
;                 const f32x4 d = *(const f32x4*)(prm + c4) + accd[n], al = *(const f32x4*)(prm + 64 + c4) + acca[n];
; { const f32x2 s0 = sigmoid2((f32x2){d[0], d[1]}), s1 = sigmoid2((f32x2){d[2], d[3]}), a0 = sigmoid2((f32x2){al[0], al[1]}), a1 = sigmoid2((f32x2){al[2], al[3]});
;                   lw[n] = (f32x4){s0.x, s0.y, s1.x, s1.y} * (-0.87503886f); av[n] = (f32x4){a0.x, a0.y, a1.x, a1.y}; }
;                 { const f32x4 vc = ld_bf4(zc + 128 + c4), vp = ld_bf4(zp + 128 + c4); vm[n] = vc + *(const f32x4*)(prm + 256 + c4) * (vp - vc); }
;                 const f32x4 kc = ld_bf4(zc + 64 + c4), kpv = ld_bf4(zp + 64 + c4);
;                 const f32x4 k = kc + *(const f32x4*)(prm + 192 + c4) * (kpv - kc);
;                 kkv[n] = k * *(const f32x4*)(prm + 320 + c4);
;                 kp[n] = k * (1.0f + (av[n] - 1.0f) * *(const f32x4*)(prm + 384 + c4));
;                 const f32x4 rc = ld_bf4(zc + c4), rp = ld_bf4(zp + c4);
;                 rm[n] = rc + *(const f32x4*)(prm + 128 + c4) * (rp - rc);
;                 const f32x4 rkw = rm[n] * kp[n] * *(const f32x4*)(prm + 448 + c4);
;                 { const f32x4 sq = kkv[n] * kkv[n]; nrm += (sq[0] + sq[1]) + (sq[2] + sq[3]); }
;                 rk += rkw[0] + rkw[1] + rkw[2] + rkw[3];
; #pragma unroll
;                 for (int j = 0; j < 4; ++j) {
;                     float x = lw[n][j];
;                     x += __int_as_float(__builtin_amdgcn_update_dpp(0, __float_as_int(x), 0x111, 0xf, 0xf, false));
;                     x += __int_as_float(__builtin_amdgcn_update_dpp(0, __float_as_int(x), 0x112, 0xf, 0xf, false));
;                     x += __int_as_float(__builtin_amdgcn_update_dpp(0, __float_as_int(x), 0x114, 0xf, 0xf, false));
;                     x += __int_as_float(__builtin_amdgcn_update_dpp(0, __float_as_int(x), 0x118, 0xf, 0xf, false));
;                     cs[n][j] = x;
;                 }
;                 if (fr == 15) *(f32x4*)(tot + tt * 64 + c4) = cs[n];
	v_pk_add_f32 v[28:29], v[40:41], v[28:29]
	s_nop 0
	v_pk_mul_f32 v[28:29], v[28:29], s[4:5] op_sel_hi:[1,0]
	v_pk_add_f32 v[30:31], v[42:43], v[30:31]
	v_exp_f32_e32 v28, v28
	v_exp_f32_e32 v29, v29
	v_mfma_f32_16x16x32_bf16 v[56:59], v[64:67], v[48:51], v[44:47]
	v_mul_f32_e64 v30, v30, s4
	v_mul_f32_e64 v31, v31, s4
	v_pk_add_f32 v[28:29], v[28:29], 1.0 op_sel_hi:[1,0]
	s_nop 0
	v_rcp_f32_e32 v32, v28
	v_rcp_f32_e32 v33, v29
	v_add3_u32 v28, v143, v36, v147
	v_add_u32_e32 v28, 0xd000, v28
	v_add_u32_e32 v29, s52, v34
	v_add_u32_e32 v34, 0x24b00, v35
	ds_read2_b64 v[52:55], v28 offset0:228 offset1:244
	ds_read2_b64 v[48:51], v28 offset0:194 offset1:212
	ds_read2_b64 v[68:71], v28 offset0:162 offset1:178
	ds_read_b128 v[44:47], v29
	ds_read_b128 v[92:95], v34
	v_add_u32_e32 v29, 0x24d00, v35
	v_add_u32_e32 v34, 0x24e00, v35
	v_exp_f32_e32 v30, v30
	v_exp_f32_e32 v31, v31
	ds_read_b128 v[96:99], v29
	ds_read_b128 v[76:79], v34
	v_add_u32_e32 v29, 0x24a00, v35
	v_add_u32_e32 v34, 0x24f00, v35
	v_pk_mul_f32 v[154:155], v[32:33], s[6:7] op_sel_hi:[1,0]
	ds_read_b128 v[64:67], v29
	ds_read_b128 v[60:63], v34
	v_pk_add_f32 v[30:31], v[30:31], 1.0 op_sel_hi:[1,0]
	v_add_f32_dpp v32, v154, v154 row_shr:1 row_mask:0xf bank_mask:0xf bound_ctrl:1
	v_add_f32_dpp v33, v155, v155 row_shr:1 row_mask:0xf bank_mask:0xf bound_ctrl:1
	v_rcp_f32_e32 v30, v30
	v_rcp_f32_e32 v31, v31
	v_add_f32_dpp v32, v32, v32 row_shr:2 row_mask:0xf bank_mask:0xf bound_ctrl:1
	v_add_f32_dpp v33, v33, v33 row_shr:2 row_mask:0xf bank_mask:0xf bound_ctrl:1
	v_pk_mul_f32 v[152:153], v[30:31], s[6:7] op_sel_hi:[1,0]
	s_nop 0
	v_add_f32_dpp v32, v32, v32 row_shr:4 row_mask:0xf bank_mask:0xf bound_ctrl:1
	v_add_f32_dpp v33, v33, v33 row_shr:4 row_mask:0xf bank_mask:0xf bound_ctrl:1
	v_add_f32_dpp v30, v152, v152 row_shr:1 row_mask:0xf bank_mask:0xf bound_ctrl:1
	v_add_f32_dpp v31, v153, v153 row_shr:1 row_mask:0xf bank_mask:0xf bound_ctrl:1
	v_add_f32_dpp v40, v32, v32 row_shr:8 row_mask:0xf bank_mask:0xf bound_ctrl:1
	v_add_f32_dpp v41, v33, v33 row_shr:8 row_mask:0xf bank_mask:0xf bound_ctrl:1
	v_add_f32_dpp v30, v30, v30 row_shr:2 row_mask:0xf bank_mask:0xf bound_ctrl:1
	v_add_f32_dpp v31, v31, v31 row_shr:2 row_mask:0xf bank_mask:0xf bound_ctrl:1
	s_nop 0
	v_add_f32_dpp v30, v30, v30 row_shr:4 row_mask:0xf bank_mask:0xf bound_ctrl:1
	v_add_f32_dpp v31, v31, v31 row_shr:4 row_mask:0xf bank_mask:0xf bound_ctrl:1
	s_nop 0
	v_add_f32_dpp v42, v30, v30 row_shr:8 row_mask:0xf bank_mask:0xf bound_ctrl:1
	v_add_f32_dpp v43, v31, v31 row_shr:8 row_mask:0xf bank_mask:0xf bound_ctrl:1
	s_and_saveexec_b64 s[20:21], s[18:19]
	ds_write_b128 v191, v[40:43]
	s_or_b64 exec, exec, s[20:21]
	v_or_b32_e32 v29, 16, v146
	v_lshl_add_u32 v190, v29, 2, 0
	v_add_u32_e32 v29, 0x24800, v190
	ds_read_b128 v[30:33], v29
	v_mov_b32_e32 v196, v127
	v_mov_b32_e32 v197, v127
	v_add_u32_e32 v29, 0x24900, v190
	ds_read_b128 v[116:119], v29
	s_waitcnt lgkmcnt(1)
	v_pk_add_f32 v[24:25], v[24:25], v[30:31]
	v_pk_add_f32 v[26:27], v[26:27], v[32:33]
	v_pk_mul_f32 v[24:25], v[24:25], s[4:5] op_sel_hi:[1,0]
	v_pk_mul_f32 v[26:27], v[26:27], s[4:5] op_sel_hi:[1,0]
	v_exp_f32_e32 v24, v24
	v_exp_f32_e32 v25, v25
	v_exp_f32_e32 v26, v26
	v_exp_f32_e32 v27, v27
	v_add_u32_e32 v29, 0x24c00, v190
	v_pk_add_f32 v[24:25], v[24:25], 1.0 op_sel_hi:[1,0]
	v_add_u32_e32 v80, 0x24b00, v190
	v_rcp_f32_e32 v24, v24
	v_rcp_f32_e32 v25, v25
	v_pk_add_f32 v[26:27], v[26:27], 1.0 op_sel_hi:[1,0]
	ds_read2_b64 v[36:39], v28 offset0:232 offset1:248
	ds_read2_b64 v[32:35], v28 offset0:198 offset1:216
	v_rcp_f32_e32 v26, v26
	v_pk_mul_f32 v[150:151], v[24:25], s[6:7] op_sel_hi:[1,0]
	v_rcp_f32_e32 v27, v27
	ds_read2_b64 v[100:103], v28 offset0:166 offset1:182
	v_add_f32_dpp v24, v150, v150 row_shr:1 row_mask:0xf bank_mask:0xf bound_ctrl:1
	v_add_f32_dpp v25, v151, v151 row_shr:1 row_mask:0xf bank_mask:0xf bound_ctrl:1
	v_pk_mul_f32 v[148:149], v[26:27], s[6:7] op_sel_hi:[1,0]
	s_nop 0
	v_add_f32_dpp v24, v24, v24 row_shr:2 row_mask:0xf bank_mask:0xf bound_ctrl:1
	v_add_f32_dpp v25, v25, v25 row_shr:2 row_mask:0xf bank_mask:0xf bound_ctrl:1
	ds_read_b128 v[28:31], v29
	ds_read_b128 v[108:111], v80
	v_add_f32_dpp v24, v24, v24 row_shr:4 row_mask:0xf bank_mask:0xf bound_ctrl:1
	v_add_f32_dpp v25, v25, v25 row_shr:4 row_mask:0xf bank_mask:0xf bound_ctrl:1
	v_add_u32_e32 v80, 0x24d00, v190
	v_add_f32_dpp v26, v148, v148 row_shr:1 row_mask:0xf bank_mask:0xf bound_ctrl:1
	v_add_f32_dpp v27, v149, v149 row_shr:1 row_mask:0xf bank_mask:0xf bound_ctrl:1
	v_add_f32_dpp v24, v24, v24 row_shr:8 row_mask:0xf bank_mask:0xf bound_ctrl:1
	v_add_f32_dpp v25, v25, v25 row_shr:8 row_mask:0xf bank_mask:0xf bound_ctrl:1
	v_add_u32_e32 v81, 0x24e00, v190
	ds_read_b128 v[112:115], v80
	ds_read_b128 v[104:107], v81
	v_add_u32_e32 v80, 0x24a00, v190
	v_add_u32_e32 v81, 0x24f00, v190
	v_add_f32_dpp v26, v26, v26 row_shr:2 row_mask:0xf bank_mask:0xf bound_ctrl:1
	v_add_f32_dpp v27, v27, v27 row_shr:2 row_mask:0xf bank_mask:0xf bound_ctrl:1
	ds_read_b128 v[88:91], v80
	ds_read_b128 v[80:83], v81
	v_add_f32_dpp v26, v26, v26 row_shr:4 row_mask:0xf bank_mask:0xf bound_ctrl:1
	v_add_f32_dpp v27, v27, v27 row_shr:4 row_mask:0xf bank_mask:0xf bound_ctrl:1
	s_nop 0
	v_add_f32_dpp v26, v26, v26 row_shr:8 row_mask:0xf bank_mask:0xf bound_ctrl:1
	v_add_f32_dpp v27, v27, v27 row_shr:8 row_mask:0xf bank_mask:0xf bound_ctrl:1
	s_and_saveexec_b64 s[20:21], s[18:19]
	ds_write_b128 v191, v[24:27] offset:64
	s_or_b64 exec, exec, s[20:21]
	v_pk_add_f32 v[74:75], v[74:75], v[86:87]
	v_pk_add_f32 v[72:73], v[72:73], v[84:85]
	v_pk_mul_f32 v[74:75], v[74:75], s[4:5] op_sel_hi:[1,0]
; __device__ __forceinline__ f32x4 ld_bf4(const bf16_t* p) { const u32x2 u = *(const u32x2*)p; return (f32x4){bf_lo(u.x), bf_hi(u.x), bf_lo(u.y), bf_hi(u.y)}; }
; __device__ __forceinline__ void phase_prep(const Params& p, unsigned char* shm) {
;     ...
; { const f32x2 s0 = sigmoid2((f32x2){d[0], d[1]}), s1 = sigmoid2((f32x2){d[2], d[3]}), a0 = sigmoid2((f32x2){al[0], al[1]}), a1 = sigmoid2((f32x2){al[2], al[3]});
;                   lw[n] = (f32x4){s0.x, s0.y, s1.x, s1.y} * (-0.87503886f); av[n] = (f32x4){a0.x, a0.y, a1.x, a1.y}; }
;                 { const f32x4 vc = ld_bf4(zc + 128 + c4), vp = ld_bf4(zp + 128 + c4); vm[n] = vc + *(const f32x4*)(prm + 256 + c4) * (vp - vc); }
;                 const f32x4 kc = ld_bf4(zc + 64 + c4), kpv = ld_bf4(zp + 64 + c4);
;                 const f32x4 k = kc + *(const f32x4*)(prm + 192 + c4) * (kpv - kc);
;                 kkv[n] = k * *(const f32x4*)(prm + 320 + c4);
;                 kp[n] = k * (1.0f + (av[n] - 1.0f) * *(const f32x4*)(prm + 384 + c4));
;                 const f32x4 rc = ld_bf4(zc + c4), rp = ld_bf4(zp + c4);
;                 rm[n] = rc + *(const f32x4*)(prm + 128 + c4) * (rp - rc);
;                 const f32x4 rkw = rm[n] * kp[n] * *(const f32x4*)(prm + 448 + c4);
;                 { const f32x4 sq = kkv[n] * kkv[n]; nrm += (sq[0] + sq[1]) + (sq[2] + sq[3]); }
;                 rk += rkw[0] + rkw[1] + rkw[2] + rkw[3];
; #pragma unroll
;                 for (int j = 0; j < 4; ++j) {
;                     float x = lw[n][j];
;                     x += __int_as_float(__builtin_amdgcn_update_dpp(0, __float_as_int(x), 0x111, 0xf, 0xf, false));
;                     x += __int_as_float(__builtin_amdgcn_update_dpp(0, __float_as_int(x), 0x112, 0xf, 0xf, false));
;                     x += __int_as_float(__builtin_amdgcn_update_dpp(0, __float_as_int(x), 0x114, 0xf, 0xf, false));
;                     x += __int_as_float(__builtin_amdgcn_update_dpp(0, __float_as_int(x), 0x118, 0xf, 0xf, false));
;                     cs[n][j] = x;
;                 }
;                 if (fr == 15) *(f32x4*)(tot + tt * 64 + c4) = cs[n];
;             }
;             nrm += __shfl_xor(nrm, 16); nrm += __shfl_xor(nrm, 32);
;             rk += __shfl_xor(rk, 16); rk += __shfl_xor(rk, 32);
;             if (fq == 0) { red[wid * 16 + fr] = nrm; red[128 + wid * 16 + fr] = rk; }
	v_pk_mul_f32 v[72:73], v[72:73], s[4:5] op_sel_hi:[1,0]
	v_exp_f32_e32 v74, v74
	v_exp_f32_e32 v75, v75
	v_exp_f32_e32 v72, v72
	v_exp_f32_e32 v73, v73
	v_lshlrev_b32_e32 v84, 16, v52
	v_pk_add_f32 v[74:75], v[74:75], 1.0 op_sel_hi:[1,0]
	v_and_b32_e32 v85, 0xffff0000, v52
	v_pk_add_f32 v[72:73], v[72:73], 1.0 op_sel_hi:[1,0]
	v_rcp_f32_e32 v74, v74
	v_rcp_f32_e32 v75, v75
	v_rcp_f32_e32 v72, v72
	v_rcp_f32_e32 v73, v73
	v_lshlrev_b32_e32 v52, 16, v53
	v_and_b32_e32 v53, 0xffff0000, v53
	v_lshlrev_b32_e32 v86, 16, v70
	v_and_b32_e32 v87, 0xffff0000, v70
	v_lshlrev_b32_e32 v70, 16, v71
	v_and_b32_e32 v71, 0xffff0000, v71
	v_sub_f32_e32 v71, v71, v53
	v_sub_f32_e32 v70, v70, v52
	v_pk_fma_f32 v[52:53], v[94:95], v[70:71], v[52:53]
	v_pk_add_f32 v[94:95], v[74:75], -1.0 op_sel_hi:[1,0]
	v_sub_f32_e32 v87, v87, v85
	v_sub_f32_e32 v86, v86, v84
	v_pk_add_f32 v[70:71], v[72:73], -1.0 op_sel_hi:[1,0]
	v_pk_fma_f32 v[78:79], v[78:79], v[94:95], 1.0 op_sel_hi:[1,1,0]
	v_pk_fma_f32 v[92:93], v[92:93], v[86:87], v[84:85]
	v_pk_mul_f32 v[84:85], v[98:99], v[52:53]
	v_pk_fma_f32 v[70:71], v[76:77], v[70:71], 1.0 op_sel_hi:[1,1,0]
	v_pk_mul_f32 v[76:77], v[52:53], v[78:79]
	v_lshlrev_b32_e32 v52, 16, v50
	v_and_b32_e32 v53, 0xffff0000, v50
	v_lshlrev_b32_e32 v78, 16, v68
	v_and_b32_e32 v68, 0xffff0000, v68
	v_pk_mul_f32 v[86:87], v[96:97], v[92:93]
	v_pk_mul_f32 v[70:71], v[92:93], v[70:71]
	v_lshlrev_b32_e32 v50, 16, v51
	v_and_b32_e32 v51, 0xffff0000, v51
	v_lshlrev_b32_e32 v92, 16, v69
	v_and_b32_e32 v79, 0xffff0000, v69
	v_sub_f32_e32 v69, v68, v53
	v_sub_f32_e32 v68, v78, v52
	v_sub_f32_e32 v79, v79, v51
	v_sub_f32_e32 v78, v92, v50
	v_pk_fma_f32 v[64:65], v[64:65], v[68:69], v[52:53]
	v_pk_fma_f32 v[66:67], v[66:67], v[78:79], v[50:51]
	v_pk_mul_f32 v[50:51], v[70:71], v[64:65]
	v_pk_mul_f32 v[52:53], v[76:77], v[66:67]
	v_pk_mul_f32 v[50:51], v[60:61], v[50:51]
	v_pk_mul_f32 v[52:53], v[62:63], v[52:53]
	v_add_f32_e32 v50, v50, v51
	v_add_f32_e32 v50, v52, v50
	v_add_f32_e32 v50, v53, v50
	v_add_f32_e32 v93, 0, v50
	s_waitcnt lgkmcnt(9)
	v_pk_add_f32 v[50:51], v[58:59], v[118:119]
	v_pk_add_f32 v[52:53], v[56:57], v[116:117]
	v_pk_mul_f32 v[50:51], v[50:51], s[4:5] op_sel_hi:[1,0]
	v_pk_mul_f32 v[52:53], v[52:53], s[4:5] op_sel_hi:[1,0]
	v_exp_f32_e32 v56, v50
	v_exp_f32_e32 v52, v52
	v_exp_f32_e32 v53, v53
	v_exp_f32_e32 v57, v51
	v_pk_mul_f32 v[60:61], v[84:85], v[84:85]
	v_pk_mul_f32 v[62:63], v[86:87], v[86:87]
	v_pk_add_f32 v[50:51], v[52:53], 1.0 op_sel_hi:[1,0]
	v_pk_add_f32 v[52:53], v[56:57], 1.0 op_sel_hi:[1,0]
	v_rcp_f32_e32 v50, v50
	v_rcp_f32_e32 v51, v51
	v_rcp_f32_e32 v52, v52
	v_rcp_f32_e32 v53, v53
	v_add_f32_e32 v62, v62, v63
	v_add_f32_e32 v60, v60, v61
	s_waitcnt lgkmcnt(8)
	v_lshlrev_b32_e32 v56, 16, v36
	v_and_b32_e32 v57, 0xffff0000, v36
	v_lshlrev_b32_e32 v36, 16, v37
	v_and_b32_e32 v37, 0xffff0000, v37
	s_waitcnt lgkmcnt(6)
	v_lshlrev_b32_e32 v58, 16, v103
	v_and_b32_e32 v59, 0xffff0000, v103
	v_add_f32_e32 v92, v62, v60
	v_lshlrev_b32_e32 v60, 16, v102
	v_and_b32_e32 v61, 0xffff0000, v102
	v_sub_f32_e32 v59, v59, v37
	v_sub_f32_e32 v58, v58, v36
	v_sub_f32_e32 v61, v61, v57
	v_sub_f32_e32 v60, v60, v56
	s_waitcnt lgkmcnt(4)
	v_pk_fma_f32 v[62:63], v[110:111], v[58:59], v[36:37]
	v_pk_add_f32 v[36:37], v[50:51], -1.0 op_sel_hi:[1,0]
	v_pk_add_f32 v[68:69], v[52:53], -1.0 op_sel_hi:[1,0]
	v_pk_fma_f32 v[56:57], v[108:109], v[60:61], v[56:57]
	s_waitcnt lgkmcnt(2)
	v_pk_fma_f32 v[68:69], v[106:107], v[68:69], 1.0 op_sel_hi:[1,1,0]
	v_pk_fma_f32 v[36:37], v[104:105], v[36:37], 1.0 op_sel_hi:[1,1,0]
	v_pk_mul_f32 v[58:59], v[114:115], v[62:63]
	v_pk_mul_f32 v[60:61], v[112:113], v[56:57]
	v_pk_mul_f32 v[36:37], v[56:57], v[36:37]
	v_pk_mul_f32 v[56:57], v[62:63], v[68:69]
	v_lshlrev_b32_e32 v62, 16, v34
	v_and_b32_e32 v63, 0xffff0000, v34
	v_lshlrev_b32_e32 v34, 16, v35
	v_and_b32_e32 v35, 0xffff0000, v35
	v_lshlrev_b32_e32 v68, 16, v100
	v_and_b32_e32 v69, 0xffff0000, v100
	v_lshlrev_b32_e32 v78, 16, v101
	v_and_b32_e32 v79, 0xffff0000, v101
	v_sub_f32_e32 v69, v69, v63
	v_sub_f32_e32 v68, v68, v62
	v_sub_f32_e32 v79, v79, v35
	v_sub_f32_e32 v78, v78, v34
	s_waitcnt lgkmcnt(1)
	v_pk_fma_f32 v[34:35], v[90:91], v[78:79], v[34:35]
	v_pk_fma_f32 v[62:63], v[88:89], v[68:69], v[62:63]
	v_pk_mul_f32 v[78:79], v[56:57], v[34:35]
	v_pk_mul_f32 v[68:69], v[36:37], v[62:63]
	s_waitcnt lgkmcnt(0)
	v_pk_mul_f32 v[78:79], v[82:83], v[78:79]
	v_pk_mul_f32 v[68:69], v[80:81], v[68:69]
	v_pk_mul_f32 v[80:81], v[58:59], v[58:59]
	v_pk_mul_f32 v[82:83], v[60:61], v[60:61]
	v_add_f32_e32 v80, v80, v81
	v_add_f32_e32 v82, v82, v83
	v_add_f32_e32 v80, v82, v80
	v_and_b32_e32 v82, 64, v180
	v_xor_b32_e32 v81, 16, v180
	v_add_u32_e32 v82, 64, v82
	v_add_f32_e32 v68, v68, v69
	v_cmp_lt_i32_e32 vcc, v81, v82
	v_add_f32_e32 v68, v78, v68
	v_add_f32_e32 v68, v79, v68
	v_cndmask_b32_e32 v81, v180, v81, vcc
	v_add_f32_e32 v80, v92, v80
	v_lshlrev_b32_e32 v81, 2, v81
	v_add_f32_e32 v68, v93, v68
	ds_bpermute_b32 v83, v81, v80
	ds_bpermute_b32 v79, v81, v68
	v_xor_b32_e32 v78, 32, v180
	v_cmp_lt_i32_e32 vcc, v78, v82
	s_ashr_i32 s71, s25, 6
	s_waitcnt lgkmcnt(1)
	v_add_f32_e32 v69, v80, v83
	v_cndmask_b32_e32 v78, v180, v78, vcc
	v_lshlrev_b32_e32 v78, 2, v78
	s_waitcnt lgkmcnt(0)
	v_add_f32_e32 v79, v68, v79
	ds_bpermute_b32 v80, v78, v69
	ds_bpermute_b32 v81, v78, v79
	v_and_b32_e32 v68, 63, v187
	s_ashr_i32 s27, s26, 31
	v_cmp_gt_u32_e32 vcc, 16, v68
	s_waitcnt lgkmcnt(1)
	v_add_f32_e32 v78, v69, v80
	s_waitcnt lgkmcnt(0)
	v_add_f32_e32 v69, v79, v81
	s_lshl_b32 s72, s71, 4
	s_and_saveexec_b64 s[20:21], vcc
	s_lshl_b32 s23, s72, 2
	s_add_i32 s23, s23, 0
	v_lshl_add_u32 v79, v185, 2, s23
	v_add_u32_e32 v79, 0x1b000, v79
	ds_write2st64_b32 v79, v78, v69 offset1:2
	s_or_b64 exec, exec, s[20:21]
	s_xor_b32 s20, s72, 64
	s_lshl_b32 s20, s20, 2
	s_add_i32 s20, s20, 0
	v_lshl_add_u32 v81, v185, 2, s20
	s_waitcnt lgkmcnt(0)
	s_barrier
; __device__ __forceinline__ void st_bf4(bf16_t* p, f32x4 v) { u32x2 u; u.x = pk_bf16(v[0], v[1]); u.y = pk_bf16(v[2], v[3]); *(u32x2*)p = u; }
; __device__ __forceinline__ void phase_prep(const Params& p, unsigned char* shm) {
;     ...
;             nrm += red[(wid ^ 4) * 16 + fr]; rk += red[128 + (wid ^ 4) * 16 + fr];
;             const float inv = 1.0f / fmaxf(sqrtf(nrm), 1e-12f);
;             p.PRK[(size_t)row * 16 + h] = rk;
; #pragma unroll
;             for (int n = 0; n < 2; ++n) {
;                 const int c4 = 32 * chh + 16 * n + 4 * fq;
;                 f32x4 pre = (f32x4){0.f, 0.f, 0.f, 0.f}, total = (f32x4){0.f, 0.f, 0.f, 0.f};
; #pragma unroll
;                 for (int t2 = 0; t2 < 4; ++t2) { const f32x4 x = *(const f32x4*)(tot + t2 * 64 + c4); total += x; if (t2 < tt) pre += x; }
;                 const f32x4 csum = pre + cs[n];
;                 f32x4 eg, eng, egm, etc; const f32x4 ncs = -csum, cml = csum - lw[n], tmc = total - csum;
; #pragma unroll
;                 for (int j = 0; j < 4; ++j) { eg[j] = __builtin_amdgcn_exp2f(csum[j]); eng[j] = __builtin_amdgcn_exp2f(ncs[j]); egm[j] = __builtin_amdgcn_exp2f(cml[j]); etc[j] = __builtin_amdgcn_exp2f(tmc[j]); }
;                 const f32x4 kkn = kkv[n] * inv, bb = kkn * av[n];
;                 const f32x4 qt = rm[n] * eg, kt = kp[n] * eng, bt = bb * eng, kkt = kkn * egm, kpp = kp[n] * etc, bpp = bb * etc;
;                 st_bf4(Qt + tk * LD + c4, qt); st_bf4(Kt + tk * LD + c4, kt); st_bf4(Bt + tk * LD + c4, bt);
;                 const u32x2 kkw = pk_bf4(kkt), vmw = pk_bf4(vm[n]), kpw = pk_bf4(kpp), bpw = pk_bf4(bpp);
;                 *(u32x2*)(KKt + tk * LD + c4) = kkw;
;                 { bf16_t* d = KKtT + c4 * LD + tk; d[0] = (bf16_t)kkw.x; d[LD] = (bf16_t)(kkw.x >> 16); d[2 * LD] = (bf16_t)kkw.y; d[3 * LD] = (bf16_t)(kkw.y >> 16); }
;                 { bf16_t* d = VmT + c4 * LD + tk; d[0] = (bf16_t)vmw.x; d[LD] = (bf16_t)(vmw.x >> 16); d[2 * LD] = (bf16_t)vmw.y; d[3 * LD] = (bf16_t)(vmw.y >> 16); }
;                 { bf16_t* d = KpT + c4 * LD + tk; d[0] = (bf16_t)kpw.x; d[LD] = (bf16_t)(kpw.x >> 16); d[2 * LD] = (bf16_t)kpw.y; d[3 * LD] = (bf16_t)(kpw.y >> 16); }
;                 { bf16_t* d = BpT + c4 * LD + tk; d[0] = (bf16_t)bpw.x; d[LD] = (bf16_t)(bpw.x >> 16); d[2 * LD] = (bf16_t)bpw.y; d[3 * LD] = (bf16_t)(bpw.y >> 16); }
	v_add_u32_e32 v81, 0x1b000, v81
	ds_read2st64_b32 v[88:89], v81 offset1:2
	v_and_b32_e32 v83, 0xffff0000, v54
	v_lshlrev_b32_e32 v79, 16, v48
	v_and_b32_e32 v48, 0xffff0000, v48
	v_lshlrev_b32_e32 v81, 16, v49
	v_and_b32_e32 v90, 0xffff0000, v49
	v_sub_f32_e32 v49, v48, v83
	s_waitcnt lgkmcnt(0)
	v_add_f32_e32 v48, v78, v88
	v_mul_f32_e32 v78, 0x4f800000, v48
	v_cmp_gt_f32_e32 vcc, s53, v48
	v_lshlrev_b32_e32 v82, 16, v54
	v_lshlrev_b32_e32 v54, 16, v55
	v_cndmask_b32_e32 v88, v48, v78, vcc
	v_sqrt_f32_e32 v91, v88
	v_and_b32_e32 v55, 0xffff0000, v55
	v_sub_f32_e32 v78, v81, v54
	v_sub_f32_e32 v48, v79, v82
	v_add_u32_e32 v81, -1, v91
	v_sub_f32_e32 v79, v90, v55
	v_fma_f32 v90, -v81, v91, v88
	v_cmp_ge_f32_e64 s[20:21], 0, v90
	v_add_u32_e32 v90, 1, v91
	v_pk_fma_f32 v[82:83], v[44:45], v[48:49], v[82:83]
	v_cndmask_b32_e64 v81, v91, v81, s[20:21]
	v_fma_f32 v91, -v90, v91, v88
	v_cmp_lt_f32_e64 s[20:21], 0, v91
	v_pk_fma_f32 v[54:55], v[46:47], v[78:79], v[54:55]
	v_or_b32_e32 v80, s24, v126
	v_cndmask_b32_e64 v81, v81, v90, s[20:21]
	v_mul_f32_e32 v90, 0x37800000, v81
	v_cndmask_b32_e32 v81, v81, v90, vcc
	v_cmp_class_f32_e32 vcc, v88, v181
	s_lshl_b32 s40, s22, 2
	v_add_f32_e32 v45, v69, v89
	v_cndmask_b32_e32 v81, v81, v88, vcc
	v_max_f32_e32 v81, 0x2b8cbccc, v81
	v_div_scale_f32 v88, s[20:21], v81, v81, 1.0
	v_rcp_f32_e32 v90, v88
	s_mov_b64 s[20:21], s[92:93]
	s_cmp_eq_u32 s28, 0
	s_cselect_b64 s[24:25], -1, 0
	v_fma_f32 v44, -v88, v90, 1.0
	v_fmac_f32_e32 v90, v44, v90
	v_div_scale_f32 v44, vcc, 1.0, v81, 1.0
	v_mul_f32_e32 v46, v44, v90
	v_fma_f32 v47, -v88, v46, v44
	v_fmac_f32_e32 v46, v47, v90
	v_fma_f32 v44, -v88, v46, v44
	v_div_fmas_f32 v44, v44, v90, v46
	v_div_fixup_f32 v44, v44, v81, 1.0
	v_ashrrev_i32_e32 v81, 31, v80
	v_lshlrev_b64 v[46:47], 6, v[80:81]
	s_waitcnt lgkmcnt(0)
	v_lshl_add_u64 v[46:47], s[20:21], 0, v[46:47]
	v_lshl_add_u64 v[46:47], v[46:47], 0, s[40:41]
	global_store_dword v[46:47], v45, off
	v_lshl_add_u32 v46, v146, 2, 0
	v_add_u32_e32 v69, 0x1b400, v46
	ds_read_b128 v[46:49], v69
	ds_read_b128 v[78:81], v69 offset:256
	s_lshl_b64 s[22:23], s[26:27], 8
	s_cmp_gt_u32 s28, 1
	ds_read_b128 v[88:91], v69 offset:512
	s_waitcnt lgkmcnt(2)
	v_pk_add_f32 v[48:49], v[48:49], 0 op_sel_hi:[1,0]
	s_cselect_b64 vcc, -1, 0
	v_cndmask_b32_e64 v93, v49, 0, s[24:25]
	v_cndmask_b32_e64 v92, v48, 0, s[24:25]
	s_waitcnt lgkmcnt(1)
	v_pk_add_f32 v[94:95], v[80:81], v[92:93]
	v_pk_add_f32 v[46:47], v[46:47], 0 op_sel_hi:[1,0]
	v_cndmask_b32_e32 v97, v93, v95, vcc
	v_cndmask_b32_e32 v96, v92, v94, vcc
	ds_read_b128 v[92:95], v69 offset:768
	v_cndmask_b32_e64 v101, v47, 0, s[24:25]
	v_cndmask_b32_e64 v100, v46, 0, s[24:25]
	v_pk_add_f32 v[46:47], v[46:47], v[78:79]
	v_pk_add_f32 v[78:79], v[78:79], v[100:101]
	s_cmp_eq_u32 s28, 3
	v_cndmask_b32_e32 v79, v101, v79, vcc
	v_cndmask_b32_e32 v78, v100, v78, vcc
	s_waitcnt lgkmcnt(1)
	v_pk_add_f32 v[98:99], v[90:91], v[96:97]
	s_cselect_b64 s[20:21], -1, 0
	v_pk_add_f32 v[48:49], v[48:49], v[80:81]
	v_pk_add_f32 v[80:81], v[46:47], v[88:89]
	v_pk_add_f32 v[46:47], v[88:89], v[78:79]
	v_pk_add_f32 v[48:49], v[48:49], v[90:91]
	v_cndmask_b32_e64 v89, v97, v99, s[20:21]
	v_cndmask_b32_e64 v88, v96, v98, s[20:21]
	v_cndmask_b32_e64 v79, v79, v47, s[20:21]
	v_cndmask_b32_e64 v78, v78, v46, s[20:21]
	s_waitcnt lgkmcnt(0)
	v_pk_add_f32 v[46:47], v[48:49], v[94:95]
	v_pk_add_f32 v[48:49], v[80:81], v[92:93]
	v_pk_add_f32 v[42:43], v[42:43], v[88:89]
	v_pk_add_f32 v[40:41], v[40:41], v[78:79]
	v_sub_f32_e32 v91, v46, v42
	v_sub_f32_e32 v79, v48, v40
	v_sub_f32_e32 v69, v47, v43
	v_sub_f32_e32 v89, v49, v41
	v_exp_f32_e32 v78, v40
	v_exp_f32_e64 v80, -v40
	v_sub_f32_e32 v40, v40, v154
	v_exp_f32_e32 v88, v79
	v_exp_f32_e32 v79, v41
	v_exp_f32_e64 v81, -v41
	v_sub_f32_e32 v41, v41, v155
	v_exp_f32_e32 v90, v42
	v_exp_f32_e64 v92, -v42
	v_sub_f32_e32 v42, v42, v152
	v_exp_f32_e32 v94, v91
	v_exp_f32_e32 v91, v43
	v_exp_f32_e64 v93, -v43
	v_sub_f32_e32 v43, v43, v153
	v_mul_u32_u24_e32 v45, 0x48, v126
	v_exp_f32_e32 v40, v40
	v_exp_f32_e32 v41, v41
	v_exp_f32_e32 v42, v42
	v_exp_f32_e32 v43, v43
	v_lshlrev_b32_e32 v45, 1, v45
	v_pk_mul_f32 v[84:85], v[84:85], v[44:45] op_sel_hi:[1,0]
	v_pk_mul_f32 v[86:87], v[86:87], v[44:45] op_sel_hi:[1,0]
	v_exp_f32_e32 v89, v89
	v_pk_mul_f32 v[72:73], v[72:73], v[86:87]
	v_pk_mul_f32 v[74:75], v[74:75], v[84:85]
	v_pk_mul_f32 v[66:67], v[66:67], v[90:91]
	v_pk_mul_f32 v[64:65], v[64:65], v[78:79]
	v_pk_mul_f32 v[78:79], v[76:77], v[92:93]
	v_pk_mul_f32 v[90:91], v[70:71], v[80:81]
	v_exp_f32_e32 v95, v69
	v_pk_mul_f32 v[92:93], v[74:75], v[92:93]
	v_pk_mul_f32 v[80:81], v[72:73], v[80:81]
	v_pk_mul_f32 v[42:43], v[84:85], v[42:43]
	v_pk_mul_f32 v[84:85], v[86:87], v[40:41]
	v_add3_u32 v40, 0, v45, v147
	v_cvt_pk_bf16_f32 v64, v64, v65
	v_cvt_pk_bf16_f32 v65, v66, v67
	v_cvt_pk_bf16_f32 v66, v90, v91
	v_cvt_pk_bf16_f32 v67, v78, v79
	ds_write2st64_b64 v40, v[64:65], v[66:67] offset0:72 offset1:90
	v_cvt_pk_bf16_f32 v64, v80, v81
	v_cvt_pk_bf16_f32 v65, v92, v93
	v_cvt_pk_bf16_f32 v66, v84, v85
	v_cvt_pk_bf16_f32 v67, v42, v43
	v_lshlrev_b32_e32 v102, 1, v126
	ds_write2st64_b64 v40, v[64:65], v[66:67] offset0:108 offset1:126
	v_mul_lo_u32 v64, v146, s50
	v_pk_mul_f32 v[70:71], v[70:71], v[88:89]
	v_pk_mul_f32 v[72:73], v[72:73], v[88:89]
	v_cvt_pk_bf16_f32 v41, v82, v83
	v_add3_u32 v42, s55, v102, v64
	v_add3_u32 v43, s56, v102, v64
	s_cmp_lg_u32 s28, 0
	v_pk_mul_f32 v[76:77], v[76:77], v[94:95]
	v_pk_mul_f32 v[74:75], v[74:75], v[94:95]
	v_cvt_pk_bf16_f32 v45, v54, v55
	v_cvt_pk_bf16_f32 v55, v70, v71
	v_cvt_pk_bf16_f32 v70, v72, v73
	ds_write_b16 v42, v66
	ds_write_b16_d16_hi v42, v66 offset:144
	ds_write_b16 v42, v67 offset:288
	ds_write_b16_d16_hi v42, v67 offset:432
	ds_write_b16 v43, v41
	ds_write_b16_d16_hi v43, v41 offset:144
	ds_write_b16 v43, v45 offset:288
	ds_write_b16_d16_hi v43, v45 offset:432
	v_add3_u32 v54, s57, v102, v64
	v_add3_u32 v41, s58, v102, v64
	v_cvt_pk_bf16_f32 v69, v76, v77
	v_cvt_pk_bf16_f32 v71, v74, v75
	ds_write_b16 v54, v55
	ds_write_b16_d16_hi v54, v55 offset:144
	ds_write_b16 v54, v69 offset:288
	ds_write_b16_d16_hi v54, v69 offset:432
	ds_write_b16 v41, v70
	ds_write_b16_d16_hi v41, v70 offset:144
	ds_write_b16 v41, v71 offset:288
	ds_write_b16_d16_hi v41, v71 offset:432
	s_cbranch_scc1 .LBB0_197
	s_mov_b64 s[30:31], s[94:95]
	v_exp_f32_e32 v64, v48
	v_exp_f32_e32 v65, v49
	v_exp_f32_e32 v66, v46
	v_exp_f32_e32 v67, v47
	s_waitcnt lgkmcnt(0)
	s_add_u32 s30, s30, s22
	v_ashrrev_i32_e32 v147, 31, v146
	s_addc_u32 s31, s31, s23
	v_lshl_add_u64 v[46:47], v[146:147], 2, s[30:31]
	global_store_dwordx4 v[46:47], v[64:67], off
